# v086 + windowed attention QK: the eight accumulator-init copies per tile deleted, second score MFMA reads the init vector directly as SrcC
# speedup vs baseline: 1.0029x; 1.0003x over previous
; template <bool WIN> ...
;     ...
;         const int k0 = (t_lo + tr) * 64;
;         const bool skip = WIN && (k0 > qw + 31 + 128 || k0 + 63 < qw - 128);
;         if (!skip) {
;             const bool near = WIN || ((k0 - (qw + 31)) < 128 && (qw - (k0 + 63)) < 128);
;             const float cinit = near ? 0.f : (k0 > qw ? cfar_hi : cfar_lo);
;             if (__builtin_expect(cinit != cbase, 0)) { cbase = cinit; asm volatile("" ::: "memory");
; #pragma unroll
;                 for (int r = 0; r < 16; ++r) cvec[r] = cbase - m_ref; }
;             f32x16 s0, s1;
;             const ALAS unsigned char* sb = lds + (tr & (NSTG - 1)) * STAGE;
;             {
;                 bf16x8 ka[8];
; #pragma unroll
;                 for (int ds = 0; ds < 4; ++ds) { ka[2 * ds] = *(const ALAS bf16x8*)(sb + kx[ds]); ka[2 * ds + 1] = *(const ALAS bf16x8*)(sb + kx[ds] + 4096); }
;                 __builtin_amdgcn_sched_barrier(0);
;                 s0 = __builtin_amdgcn_mfma_f32_32x32x16_bf16(ka[0], qf(0), cvec, 0, 0, 0);
;                 s1 = __builtin_amdgcn_mfma_f32_32x32x16_bf16(ka[1], qf(0), cvec, 0, 0, 0);
; #pragma unroll
;                 for (int ds = 1; ds < 4; ++ds) {
;                     s0 = __builtin_amdgcn_mfma_f32_32x32x16_bf16(ka[2 * ds], qf(ds), s0, 0, 0, 0);
;                     s1 = __builtin_amdgcn_mfma_f32_32x32x16_bf16(ka[2 * ds + 1], qf(ds), s1, 0, 0, 0);
;                 }
;             }
;             bf16x8 va[2 * NDB], vc[2 * NDB];
; #pragma unroll
;             for (int kk = 0; kk < 2; ++kk)
; #pragma unroll
;                 for (int db = 0; db < NDB; ++db) va[kk * NDB + db] = *(const ALAS bf16x8*)(sb + vx[kk] + db * 4096);
;             __builtin_amdgcn_sched_barrier(0);
;             if (near) {
;                 const ALAS float* lb = lut + (k0 + 8 * hi - qabs + LUTC);
; #pragma unroll
;                 for (int r = 0; r < 16; ++r) { s0[r] += lb[16 * (r >> 3) + (r & 7)]; s1[r] += lb[32 + 16 * (r >> 3) + (r & 7)];
;                     if ((r & 7) == 7) __builtin_amdgcn_sched_barrier(0); }
;             }
;     ...
;             float mxa = MX3(s0[0], s0[1], s1[0]), mxb = MX3(s0[2], s0[3], s1[1]);
;             mxa = MX3(mxa, s1[2], s1[3]);
; #pragma unroll
;             for (int r = 4; r < 16; r += 4) { mxa = MX3(mxa, s0[r], s0[r + 1]); mxb = MX3(mxb, s0[r + 2], s0[r + 3]); mxa = MX3(mxa, s1[r], s1[r + 1]); mxb = MX3(mxb, s1[r + 2], s1[r + 3]); }
.LBB0_306:
	s_cmp_gt_i32 s50, s31
	s_cselect_b64 s[48:49], -1, 0
	s_add_i32 s53, s50, 63
	s_cmp_lt_i32 s53, s33
	s_cselect_b64 s[54:55], -1, 0
	s_or_b64 s[48:49], s[48:49], s[54:55]
	s_and_b64 vcc, exec, s[48:49]
	s_cbranch_vccnz .LBB0_301
	s_and_b32 s48, s51, 0x18000
	s_add_i32 s48, s48, 0
	v_add3_u32 v52, s48, v178, v177
	ds_read_b128 v[48:51], v52
	ds_read_b128 v[96:99], v52 offset:4096
	v_add3_u32 v52, s48, v180, v177
	ds_read_b128 v[100:103], v52
	ds_read_b128 v[104:107], v52 offset:4096
	v_add3_u32 v52, s48, v182, v177
	ds_read_b128 v[108:111], v52
	ds_read_b128 v[122:125], v52 offset:4096
	v_add3_u32 v52, s48, v184, v177
	ds_read_b128 v[126:129], v52
	ds_read_b128 v[136:139], v52 offset:4096
	s_waitcnt lgkmcnt(7)
	v_mfma_f32_32x32x16_bf16 v[64:79], v[48:51], v[80:83], v[32:47]
	s_waitcnt lgkmcnt(5)
	v_mfma_f32_32x32x16_bf16 v[64:79], v[100:103], v[84:87], v[64:79]
	v_mfma_f32_32x32x16_bf16 v[48:63], v[96:99], v[80:83], v[32:47]
	v_add3_u32 v96, s48, v179, v187
	s_waitcnt lgkmcnt(4)
	v_mfma_f32_32x32x16_bf16 v[48:63], v[104:107], v[84:87], v[48:63]
	s_waitcnt lgkmcnt(3)
	v_mfma_f32_32x32x16_bf16 v[64:79], v[108:111], v[88:91], v[64:79]
	ds_read_b128 v[108:111], v96 offset:16384
	ds_read_b128 v[104:107], v96 offset:20480
	v_add3_u32 v96, s48, v181, v187
	ds_read_b128 v[100:103], v96 offset:16384
	ds_read_b128 v[96:99], v96 offset:20480
	s_waitcnt lgkmcnt(6)
	v_mfma_f32_32x32x16_bf16 v[48:63], v[122:125], v[88:91], v[48:63]
	s_waitcnt lgkmcnt(5)
	v_mfma_f32_32x32x16_bf16 v[64:79], v[126:129], v[92:95], v[64:79]
	s_waitcnt lgkmcnt(4)
	v_mfma_f32_32x32x16_bf16 v[48:63], v[136:139], v[92:95], v[48:63]
	ds_read2_b32 v[122:123], v117 offset1:1
	ds_read2_b32 v[124:125], v117 offset0:32 offset1:33
	ds_read2_b32 v[126:127], v117 offset0:2 offset1:3
	ds_read2_b32 v[128:129], v117 offset0:4 offset1:5
	ds_read2_b32 v[136:137], v117 offset0:6 offset1:7
	ds_read2_b32 v[138:139], v117 offset0:34 offset1:35
	ds_read2_b32 v[140:141], v117 offset0:36 offset1:37
	ds_read2_b32 v[142:143], v117 offset0:38 offset1:39
	s_waitcnt lgkmcnt(7)
	s_nop 0
	v_pk_add_f32 v[122:123], v[64:65], v[122:123]
	s_waitcnt lgkmcnt(6)
	v_pk_add_f32 v[64:65], v[48:49], v[124:125]
	s_waitcnt lgkmcnt(5)
	v_pk_add_f32 v[124:125], v[66:67], v[126:127]
	s_waitcnt lgkmcnt(2)
	v_pk_add_f32 v[48:49], v[50:51], v[138:139]
	v_pk_add_f32 v[126:127], v[68:69], v[128:129]
	s_waitcnt lgkmcnt(1)
	v_pk_add_f32 v[50:51], v[52:53], v[140:141]
	v_pk_add_f32 v[128:129], v[70:71], v[136:137]
	s_waitcnt lgkmcnt(0)
	v_pk_add_f32 v[52:53], v[54:55], v[142:143]
	ds_read2_b32 v[54:55], v117 offset0:16 offset1:17
	ds_read2_b32 v[68:69], v117 offset0:48 offset1:49
	ds_read2_b32 v[70:71], v117 offset0:18 offset1:19
	ds_read2_b32 v[136:137], v117 offset0:20 offset1:21
	ds_read2_b32 v[138:139], v117 offset0:22 offset1:23
	s_waitcnt lgkmcnt(4)
	v_pk_add_f32 v[66:67], v[72:73], v[54:55]
	ds_read2_b32 v[54:55], v117 offset0:50 offset1:51
	ds_read2_b32 v[140:141], v117 offset0:52 offset1:53
	ds_read2_b32 v[142:143], v117 offset0:54 offset1:55
	s_waitcnt lgkmcnt(6)
	v_pk_add_f32 v[56:57], v[56:57], v[68:69]
	s_waitcnt lgkmcnt(5)
	v_pk_add_f32 v[72:73], v[74:75], v[70:71]
	s_waitcnt lgkmcnt(2)
	v_pk_add_f32 v[58:59], v[58:59], v[54:55]
	v_pk_add_f32 v[68:69], v[76:77], v[136:137]
	s_waitcnt lgkmcnt(1)
	v_pk_add_f32 v[54:55], v[60:61], v[140:141]
	v_pk_add_f32 v[70:71], v[78:79], v[138:139]
	s_waitcnt lgkmcnt(0)
	v_pk_add_f32 v[60:61], v[62:63], v[142:143]
	v_max_f32_e32 v62, v122, v123
	v_max3_f32 v63, v124, v125, v65
	v_max3_f32 v62, v62, v64, v48
	v_max3_f32 v62, v62, v49, v126
	v_max3_f32 v63, v63, v128, v129
	v_max3_f32 v62, v62, v127, v50
	v_max3_f32 v63, v63, v52, v53
	v_max3_f32 v62, v62, v51, v66
	v_max3_f32 v63, v63, v72, v73
	v_max3_f32 v62, v62, v67, v56
	v_max3_f32 v63, v63, v58, v59
	v_max3_f32 v62, v62, v57, v68
	v_max3_f32 v63, v63, v70, v71
	v_max3_f32 v62, v62, v69, v54
	v_max3_f32 v63, v63, v60, v61
	v_max3_f32 v62, v62, v55, v63
	v_cmp_lt_f32_e32 vcc, s26, v62
	s_cbranch_vccz .LBB0_300
	ds_bpermute_b32 v32, v176, v62
	s_waitcnt lgkmcnt(0)
	v_max3_f32 v33, v62, v32, 0
	v_exp_f32_e64 v34, -v33
	v_add_f32_e32 v134, v134, v33
	v_sub_f32_e32 v32, 0, v134
	v_sub_f32_e32 v122, v122, v33
	v_sub_f32_e32 v123, v123, v33
	v_sub_f32_e32 v124, v124, v33
	v_sub_f32_e32 v125, v125, v33
	v_sub_f32_e32 v126, v126, v33
	v_sub_f32_e32 v127, v127, v33
	v_sub_f32_e32 v128, v128, v33
	v_sub_f32_e32 v129, v129, v33
	v_sub_f32_e32 v66, v66, v33
	v_sub_f32_e32 v67, v67, v33
	v_sub_f32_e32 v72, v72, v33
	v_sub_f32_e32 v73, v73, v33
	v_sub_f32_e32 v68, v68, v33
	v_sub_f32_e32 v69, v69, v33
	v_sub_f32_e32 v70, v70, v33
	v_sub_f32_e32 v71, v71, v33
	v_sub_f32_e32 v64, v64, v33
	v_sub_f32_e32 v65, v65, v33
	v_sub_f32_e32 v48, v48, v33
	v_sub_f32_e32 v49, v49, v33
	v_sub_f32_e32 v50, v50, v33
	v_sub_f32_e32 v51, v51, v33
	v_sub_f32_e32 v52, v52, v33
	v_sub_f32_e32 v53, v53, v33
	v_sub_f32_e32 v56, v56, v33
	v_sub_f32_e32 v57, v57, v33
	v_sub_f32_e32 v58, v58, v33
	v_sub_f32_e32 v59, v59, v33
	v_sub_f32_e32 v54, v54, v33
	v_sub_f32_e32 v55, v55, v33
	v_sub_f32_e32 v60, v60, v33
	v_sub_f32_e32 v61, v61, v33
	v_pk_mul_f32 v[14:15], v[14:15], v[34:35] op_sel_hi:[1,0]
	v_pk_mul_f32 v[12:13], v[12:13], v[34:35] op_sel_hi:[1,0]
	v_pk_mul_f32 v[10:11], v[10:11], v[34:35] op_sel_hi:[1,0]
	v_pk_mul_f32 v[8:9], v[8:9], v[34:35] op_sel_hi:[1,0]
	v_pk_mul_f32 v[6:7], v[6:7], v[34:35] op_sel_hi:[1,0]
	v_pk_mul_f32 v[4:5], v[4:5], v[34:35] op_sel_hi:[1,0]
	v_pk_mul_f32 v[2:3], v[2:3], v[34:35] op_sel_hi:[1,0]
	v_pk_mul_f32 v[0:1], v[0:1], v[34:35] op_sel_hi:[1,0]
	v_pk_mul_f32 v[30:31], v[30:31], v[34:35] op_sel_hi:[1,0]
	v_pk_mul_f32 v[28:29], v[28:29], v[34:35] op_sel_hi:[1,0]
	v_pk_mul_f32 v[26:27], v[26:27], v[34:35] op_sel_hi:[1,0]
	v_pk_mul_f32 v[24:25], v[24:25], v[34:35] op_sel_hi:[1,0]
	v_pk_mul_f32 v[22:23], v[22:23], v[34:35] op_sel_hi:[1,0]
	v_pk_mul_f32 v[20:21], v[20:21], v[34:35] op_sel_hi:[1,0]
	v_pk_mul_f32 v[18:19], v[18:19], v[34:35] op_sel_hi:[1,0]
	v_pk_mul_f32 v[16:17], v[16:17], v[34:35] op_sel_hi:[1,0]
	v_mul_f32_e32 v112, v112, v34
	v_mov_b32_e32 v33, v32
	v_mov_b32_e32 v34, v32
	v_mov_b32_e32 v35, v32
	v_mov_b32_e32 v36, v32
	v_mov_b32_e32 v37, v32
	v_mov_b32_e32 v38, v32
	v_mov_b32_e32 v39, v32
	v_mov_b32_e32 v40, v32
	v_mov_b32_e32 v41, v32
	v_mov_b32_e32 v42, v32
	v_mov_b32_e32 v43, v32
	v_mov_b32_e32 v44, v32
	v_mov_b32_e32 v45, v32
	v_mov_b32_e32 v46, v32
	v_mov_b32_e32 v47, v32
	s_branch .LBB0_300
